# in-proj cq/ckv/krr epilogue paths widened to dwordx4 stores; last-layer MLP-down uses the hand-written residual epilogue (no next-norm)
# speedup vs baseline: 1.0094x; 1.0094x over previous
.Lresid_nonorm:
	v_readlane_b32 s62, v252, 7
	v_readlane_b32 s63, v252, 8
	s_lshr_b32 s20, s56, 4
	s_mul_i32 s20, s20, 0x6000
	s_add_u32 s44, s66, s20
	s_addc_u32 s45, s12, 0
	s_add_u32 s46, s13, s20
	s_addc_u32 s47, s26, 0
	s_mov_b32 s60, s38
	s_mov_b32 s61, s95
	v_lshl_or_b32 v236, s57, 8, v246
	v_lshl_add_u32 v237, s56, 8, v244
	v_lshlrev_b32_e32 v210, 2, v236
	v_lshl_add_u32 v211, v237, 12, v210
	v_and_b32_e32 v212, 4, v246
	v_mul_u32_u24_e32 v212, 6, v212
	v_lshl_add_u32 v212, v236, 1, v212
	v_lshl_add_u32 v212, v237, 11, v212
	v_lshlrev_b32_e32 v213, 2, v237
	v_lshlrev_b32_e32 v214, 2, v231
	v_lshlrev_b32_e32 v215, 2, v232
	global_load_dwordx4 v[60:63], v210, s[44:45] offset:0
	global_load_dwordx4 v[64:67], v210, s[44:45] offset:64
	global_load_dwordx4 v[68:71], v210, s[44:45] offset:512
	global_load_dwordx4 v[72:75], v210, s[44:45] offset:576
	s_mov_b32 s72, s60
	s_mov_b32 s73, s61
	global_load_dwordx4 v[164:167], v211, s[72:73] offset:0
	global_load_dwordx4 v[168:171], v211, s[72:73] offset:64
	global_load_dwordx4 v[172:175], v211, s[72:73] offset:512
	global_load_dwordx4 v[176:179], v211, s[72:73] offset:576
	s_add_u32 s72, s60, 0x10000
	s_addc_u32 s73, s61, 0
	global_load_dwordx4 v[194:197], v211, s[72:73] offset:0
	global_load_dwordx4 v[198:201], v211, s[72:73] offset:64
	global_load_dwordx4 v[202:205], v211, s[72:73] offset:512
	global_load_dwordx4 v[206:209], v211, s[72:73] offset:576
	s_waitcnt vmcnt(4)
	s_mov_b32 s74, s62
	s_mov_b32 s75, s63
	v_pk_fma_f32 v[164:165], v[144:145], v[60:61], v[164:165]
	v_pk_fma_f32 v[166:167], v[146:147], v[62:63], v[166:167]
	global_store_dwordx4 v211, v[164:167], s[74:75] offset:0
	v_pk_fma_f32 v[168:169], v[140:141], v[64:65], v[168:169]
	v_pk_fma_f32 v[170:171], v[142:143], v[66:67], v[170:171]
	global_store_dwordx4 v211, v[168:171], s[74:75] offset:64
	v_pk_fma_f32 v[172:173], v[136:137], v[68:69], v[172:173]
	v_pk_fma_f32 v[174:175], v[138:139], v[70:71], v[174:175]
	global_store_dwordx4 v211, v[172:175], s[74:75] offset:512
	v_pk_fma_f32 v[176:177], v[132:133], v[72:73], v[176:177]
	v_pk_fma_f32 v[178:179], v[134:135], v[74:75], v[178:179]
	global_store_dwordx4 v211, v[176:179], s[74:75] offset:576
	s_add_u32 s72, s60, 0x20000
	s_addc_u32 s73, s61, 0
	global_load_dwordx4 v[164:167], v211, s[72:73] offset:0
	global_load_dwordx4 v[168:171], v211, s[72:73] offset:64
	global_load_dwordx4 v[172:175], v211, s[72:73] offset:512
	global_load_dwordx4 v[176:179], v211, s[72:73] offset:576
	s_add_u32 s72, s60, 0x30000
	s_addc_u32 s73, s61, 0
	global_load_dwordx4 v[144:147], v211, s[72:73] offset:0
	global_load_dwordx4 v[140:143], v211, s[72:73] offset:64
	global_load_dwordx4 v[136:139], v211, s[72:73] offset:512
	global_load_dwordx4 v[132:135], v211, s[72:73] offset:576
	s_waitcnt vmcnt(12)
	s_add_u32 s74, s62, 0x10000
	s_addc_u32 s75, s63, 0
	v_pk_fma_f32 v[194:195], v[128:129], v[60:61], v[194:195]
	v_pk_fma_f32 v[196:197], v[130:131], v[62:63], v[196:197]
	global_store_dwordx4 v211, v[194:197], s[74:75] offset:0
	v_pk_fma_f32 v[198:199], v[124:125], v[64:65], v[198:199]
	v_pk_fma_f32 v[200:201], v[126:127], v[66:67], v[200:201]
	global_store_dwordx4 v211, v[198:201], s[74:75] offset:64
	v_pk_fma_f32 v[202:203], v[120:121], v[68:69], v[202:203]
	v_pk_fma_f32 v[204:205], v[122:123], v[70:71], v[204:205]
	global_store_dwordx4 v211, v[202:205], s[74:75] offset:512
	v_pk_fma_f32 v[206:207], v[116:117], v[72:73], v[206:207]
	v_pk_fma_f32 v[208:209], v[118:119], v[74:75], v[208:209]
	global_store_dwordx4 v211, v[206:209], s[74:75] offset:576
	s_add_u32 s72, s60, 0x80000
	s_addc_u32 s73, s61, 0
	global_load_dwordx4 v[194:197], v211, s[72:73] offset:0
	global_load_dwordx4 v[198:201], v211, s[72:73] offset:64
	global_load_dwordx4 v[202:205], v211, s[72:73] offset:512
	global_load_dwordx4 v[206:209], v211, s[72:73] offset:576
	s_add_u32 s72, s60, 0x90000
	s_addc_u32 s73, s61, 0
	global_load_dwordx4 v[128:131], v211, s[72:73] offset:0
	global_load_dwordx4 v[124:127], v211, s[72:73] offset:64
	global_load_dwordx4 v[120:123], v211, s[72:73] offset:512
	global_load_dwordx4 v[116:119], v211, s[72:73] offset:576
	s_waitcnt vmcnt(16)
	s_add_u32 s74, s62, 0x20000
	s_addc_u32 s75, s63, 0
	v_pk_fma_f32 v[164:165], v[112:113], v[60:61], v[164:165]
	v_pk_fma_f32 v[166:167], v[114:115], v[62:63], v[166:167]
	global_store_dwordx4 v211, v[164:167], s[74:75] offset:0
	v_pk_fma_f32 v[168:169], v[108:109], v[64:65], v[168:169]
	v_pk_fma_f32 v[170:171], v[110:111], v[66:67], v[170:171]
	global_store_dwordx4 v211, v[168:171], s[74:75] offset:64
	v_pk_fma_f32 v[172:173], v[104:105], v[68:69], v[172:173]
	v_pk_fma_f32 v[174:175], v[106:107], v[70:71], v[174:175]
	global_store_dwordx4 v211, v[172:175], s[74:75] offset:512
	v_pk_fma_f32 v[176:177], v[100:101], v[72:73], v[176:177]
	v_pk_fma_f32 v[178:179], v[102:103], v[74:75], v[178:179]
	global_store_dwordx4 v211, v[176:179], s[74:75] offset:576
	s_add_u32 s72, s60, 0xa0000
	s_addc_u32 s73, s61, 0
	global_load_dwordx4 v[164:167], v211, s[72:73] offset:0
	global_load_dwordx4 v[168:171], v211, s[72:73] offset:64
	global_load_dwordx4 v[172:175], v211, s[72:73] offset:512
	global_load_dwordx4 v[176:179], v211, s[72:73] offset:576
	s_add_u32 s72, s60, 0xb0000
	s_addc_u32 s73, s61, 0
	global_load_dwordx4 v[112:115], v211, s[72:73] offset:0
	global_load_dwordx4 v[108:111], v211, s[72:73] offset:64
	global_load_dwordx4 v[104:107], v211, s[72:73] offset:512
	global_load_dwordx4 v[100:103], v211, s[72:73] offset:576
	s_waitcnt vmcnt(24)
	s_add_u32 s74, s62, 0x30000
	s_addc_u32 s75, s63, 0
	v_pk_fma_f32 v[144:145], v[92:93], v[60:61], v[144:145]
	v_pk_fma_f32 v[146:147], v[94:95], v[62:63], v[146:147]
	global_store_dwordx4 v211, v[144:147], s[74:75] offset:0
	v_pk_fma_f32 v[140:141], v[88:89], v[64:65], v[140:141]
	v_pk_fma_f32 v[142:143], v[90:91], v[66:67], v[142:143]
	global_store_dwordx4 v211, v[140:143], s[74:75] offset:64
	v_pk_fma_f32 v[136:137], v[84:85], v[68:69], v[136:137]
	v_pk_fma_f32 v[138:139], v[86:87], v[70:71], v[138:139]
	global_store_dwordx4 v211, v[136:139], s[74:75] offset:512
	v_pk_fma_f32 v[132:133], v[80:81], v[72:73], v[132:133]
	v_pk_fma_f32 v[134:135], v[82:83], v[74:75], v[134:135]
	global_store_dwordx4 v211, v[132:135], s[74:75] offset:576
	s_waitcnt vmcnt(20)
	s_add_u32 s74, s62, 0x80000
	s_addc_u32 s75, s63, 0
	v_pk_fma_f32 v[194:195], v[76:77], v[60:61], v[194:195]
	v_pk_fma_f32 v[196:197], v[78:79], v[62:63], v[196:197]
	global_store_dwordx4 v211, v[194:197], s[74:75] offset:0
	v_pk_fma_f32 v[198:199], v[56:57], v[64:65], v[198:199]
	v_pk_fma_f32 v[200:201], v[58:59], v[66:67], v[200:201]
	global_store_dwordx4 v211, v[198:201], s[74:75] offset:64
	v_pk_fma_f32 v[202:203], v[52:53], v[68:69], v[202:203]
	v_pk_fma_f32 v[204:205], v[54:55], v[70:71], v[204:205]
	global_store_dwordx4 v211, v[202:205], s[74:75] offset:512
	v_pk_fma_f32 v[206:207], v[48:49], v[72:73], v[206:207]
	v_pk_fma_f32 v[208:209], v[50:51], v[74:75], v[208:209]
	global_store_dwordx4 v211, v[206:209], s[74:75] offset:576
	s_waitcnt vmcnt(20)
	s_add_u32 s74, s62, 0x90000
	s_addc_u32 s75, s63, 0
	v_pk_fma_f32 v[128:129], v[44:45], v[60:61], v[128:129]
	v_pk_fma_f32 v[130:131], v[46:47], v[62:63], v[130:131]
	global_store_dwordx4 v211, v[128:131], s[74:75] offset:0
	v_pk_fma_f32 v[124:125], v[40:41], v[64:65], v[124:125]
	v_pk_fma_f32 v[126:127], v[42:43], v[66:67], v[126:127]
	global_store_dwordx4 v211, v[124:127], s[74:75] offset:64
	v_pk_fma_f32 v[120:121], v[36:37], v[68:69], v[120:121]
	v_pk_fma_f32 v[122:123], v[38:39], v[70:71], v[122:123]
	global_store_dwordx4 v211, v[120:123], s[74:75] offset:512
	v_pk_fma_f32 v[116:117], v[32:33], v[72:73], v[116:117]
	v_pk_fma_f32 v[118:119], v[34:35], v[74:75], v[118:119]
	global_store_dwordx4 v211, v[116:119], s[74:75] offset:576
	s_waitcnt vmcnt(16)
	s_add_u32 s74, s62, 0xa0000
	s_addc_u32 s75, s63, 0
	v_pk_fma_f32 v[164:165], v[28:29], v[60:61], v[164:165]
	v_pk_fma_f32 v[166:167], v[30:31], v[62:63], v[166:167]
	global_store_dwordx4 v211, v[164:167], s[74:75] offset:0
	v_pk_fma_f32 v[168:169], v[24:25], v[64:65], v[168:169]
	v_pk_fma_f32 v[170:171], v[26:27], v[66:67], v[170:171]
	global_store_dwordx4 v211, v[168:171], s[74:75] offset:64
	v_pk_fma_f32 v[172:173], v[20:21], v[68:69], v[172:173]
	v_pk_fma_f32 v[174:175], v[22:23], v[70:71], v[174:175]
	global_store_dwordx4 v211, v[172:175], s[74:75] offset:512
	v_pk_fma_f32 v[176:177], v[16:17], v[72:73], v[176:177]
	v_pk_fma_f32 v[178:179], v[18:19], v[74:75], v[178:179]
	global_store_dwordx4 v211, v[176:179], s[74:75] offset:576
	s_waitcnt vmcnt(16)
	s_add_u32 s74, s62, 0xb0000
	s_addc_u32 s75, s63, 0
	v_pk_fma_f32 v[112:113], v[12:13], v[60:61], v[112:113]
	v_pk_fma_f32 v[114:115], v[14:15], v[62:63], v[114:115]
	global_store_dwordx4 v211, v[112:115], s[74:75] offset:0
	v_pk_fma_f32 v[108:109], v[8:9], v[64:65], v[108:109]
	v_pk_fma_f32 v[110:111], v[10:11], v[66:67], v[110:111]
	global_store_dwordx4 v211, v[108:111], s[74:75] offset:64
	v_pk_fma_f32 v[104:105], v[4:5], v[68:69], v[104:105]
	v_pk_fma_f32 v[106:107], v[6:7], v[70:71], v[106:107]
	global_store_dwordx4 v211, v[104:107], s[74:75] offset:512
	v_pk_fma_f32 v[100:101], v[0:1], v[72:73], v[100:101]
	v_pk_fma_f32 v[102:103], v[2:3], v[74:75], v[102:103]
	global_store_dwordx4 v211, v[100:103], s[74:75] offset:576
	s_branch .Lresid_done

.LBB0_1056:
	s_mul_i32 s10, s79, 0x12000
	v_readlane_b32 s14, v255, 21
	s_mul_hi_i32 s9, s79, 0x12000
	v_readlane_b32 s15, v255, 22
	s_add_u32 s10, s14, s10
	s_addc_u32 s9, s15, s9
	s_add_u32 s22, s10, 0x1bc00000
	s_addc_u32 s71, s9, 0
	s_and_b32 s12, s7, 3
	s_add_i32 m0, s65, 0x18000
	v_lshl_add_u64 v[6:7], v[6:7], 0, s[30:31]
	s_lshl_b32 s7, s6, 13
	s_lshl_b32 s92, s12, 5
	s_lshl_b32 s9, s12, 12
	s_waitcnt vmcnt(2)
	s_barrier
	global_load_lds_dwordx4 v[6:7], off
	v_lshl_add_u64 v[4:5], v[4:5], 0, s[30:31]
	s_add_i32 m0, s65, 0x1a000
	s_add_i32 s93, s65, 0x8000
	s_add_i32 s94, s65, 0xa000
	global_load_lds_dwordx4 v[4:5], off
	v_lshl_add_u64 v[0:1], v[0:1], 0, s[30:31]
	s_mov_b32 m0, s93
	s_add_u32 s10, s18, 0x40080
	global_load_lds_dwordx4 v[0:1], off
	v_lshl_add_u64 v[0:1], v[2:3], 0, s[30:31]
	s_mov_b32 m0, s94
	s_addc_u32 s11, s19, 0
	global_load_lds_dwordx4 v[0:1], off
	s_add_i32 m0, s65, 0x1c000
	v_lshl_add_u64 v[0:1], s[10:11], 0, v[172:173]
	global_load_lds_dwordx4 v[0:1], off
	v_lshl_add_u64 v[0:1], s[10:11], 0, v[96:97]
	s_add_i32 m0, s65, 0x1e000
	v_bfe_u32 v2, v186, 4, 2
	global_load_lds_dwordx4 v[0:1], off
	v_and_b32_e32 v1, 15, v186
	v_lshlrev_b32_e32 v0, 4, v2
	v_lshlrev_b32_e32 v3, 2, v186
	v_lshl_or_b32 v175, s6, 6, v1
	v_lshl_or_b32 v1, v1, 6, v0
	v_and_b32_e32 v3, 32, v3
	s_cmpk_lt_u32 s8, 0x100
	v_bitop3_b32 v4, v1, s7, v3 bitop3:0xde
	s_cselect_b64 s[6:7], -1, 0
	s_bitcmp0_b32 s8, 6
	s_cselect_b64 s[38:39], -1, 0
	s_cmp_eq_u32 s12, 0
	v_bitop3_b32 v187, s9, v1, v3 bitop3:0xf6
	s_cselect_b64 s[8:9], -1, 0
	s_lshl_b32 s12, s12, 6
	v_readlane_b32 s10, v255, 39
	s_add_u32 s10, s10, s12
	v_readlane_b32 s11, v255, 40
	v_lshlrev_b32_e32 v174, 2, v2
	v_and_b32_e32 v228, 4, v174
	v_mul_u32_u24_e32 v228, 6, v228
	v_mov_b32_e32 v229, 0
	v_cmp_eq_u32_e64 s[40:41], 0, v2
	v_cmp_gt_u32_e64 s[42:43], 2, v2
	s_addc_u32 s11, s11, 0
	v_lshlrev_b32_e32 v2, 3, v2
	v_mov_b32_e32 v3, v99
	v_lshl_add_u64 v[176:177], s[10:11], 0, v[2:3]
	v_lshl_add_u64 v[176:177], v[176:177], 0, v[228:229]
	v_mov_b32_e32 v1, v99
	v_readlane_b32 s10, v255, 35
	v_lshl_add_u64 v[188:189], s[14:15], 0, v[0:1]
	v_and_b32_e32 v0, 16, v0
	v_readlane_b32 s11, v255, 36
	s_waitcnt vmcnt(6)
	v_add_u32_e32 v238, 0xb0, v175
	s_mov_b32 s95, 0
	v_lshl_add_u64 v[190:191], s[10:11], 0, v[0:1]
	v_lshlrev_b32_e32 v0, 14, v8
	v_and_b32_e32 v0, 0xffff8000, v0
	v_lshl_add_u32 v0, v9, 11, v0
	v_and_b32_e32 v1, 1, v8
	v_lshl_or_b32 v0, v1, 6, v0
	v_readlane_b32 s10, v255, 37
	v_lshl_add_u32 v194, v10, 1, v0
	v_lshlrev_b32_e32 v0, 14, v11
	s_add_u32 s10, s10, s12
	v_readlane_b32 s11, v255, 38
	v_and_b32_e32 v0, 0xffff8000, v0
	s_addc_u32 s11, s11, 0
	v_lshl_add_u32 v0, v12, 11, v0
	v_and_b32_e32 v1, 1, v11
	v_lshl_add_u64 v[192:193], s[10:11], 0, v[2:3]
	v_lshl_add_u64 v[192:193], v[192:193], 0, v[228:229]
	v_lshl_or_b32 v0, v1, 6, v0
	v_readlane_b32 s10, v254, 21
	v_lshl_add_u64 v[178:179], s[26:27], 0, v[2:3]
	v_lshl_add_u64 v[178:179], v[178:179], 0, v[228:229]
	v_mov_b32_e32 v195, v99
	v_lshl_add_u32 v196, v13, 1, v0
	v_mov_b32_e32 v197, v99
	v_add_u32_e32 v239, 0, v4
	s_lshl_b32 s36, s92, 2
	v_lshlrev_b32_e32 v240, 2, v174
	v_readlane_b32 s24, v254, 11
	s_mov_b32 s25, s10
	s_barrier
	v_readlane_b32 s11, v254, 22
	s_branch .LBB0_1059

.LBB0_1068:
	s_waitcnt vmcnt(0)
	v_fmamk_f32 v98, v164, 0x3a800000, v223
	v_mul_f32_e32 v164, 0x4b800000, v98
	v_cmp_gt_f32_e32 vcc, s29, v98
	s_cmp_gt_i32 s24, 5
	s_cselect_b64 s[52:53], -1, 0
	v_cndmask_b32_e32 v98, v98, v164, vcc
	v_rsq_f32_e32 v98, v98
	s_cmp_lg_u32 s24, 6
	s_cselect_b64 s[60:61], -1, 0
	s_cmp_lt_i32 s24, 2
	v_mul_f32_e32 v164, 0x45800000, v98
	v_cndmask_b32_e32 v98, v98, v164, vcc
	s_cselect_b64 s[56:57], -1, 0
	s_cmp_eq_u32 s24, 3
	s_cselect_b64 s[48:49], -1, 0
	v_pk_fma_f32 v[216:217], v[146:147], v[98:99], v[54:55] op_sel_hi:[1,0,1]
	v_pk_fma_f32 v[214:215], v[144:145], v[98:99], v[52:53] op_sel_hi:[1,0,1]
	v_pk_fma_f32 v[220:221], v[126:127], v[98:99], v[50:51] op_sel_hi:[1,0,1]
	v_pk_fma_f32 v[218:219], v[124:125], v[98:99], v[48:49] op_sel_hi:[1,0,1]
	v_pk_fma_f32 v[166:167], v[14:15], v[98:99], v[46:47] op_sel_hi:[1,0,1]
	v_pk_fma_f32 v[164:165], v[12:13], v[98:99], v[44:45] op_sel_hi:[1,0,1]
	v_pk_fma_f32 v[170:171], v[10:11], v[98:99], v[42:43] op_sel_hi:[1,0,1]
	v_pk_fma_f32 v[168:169], v[8:9], v[98:99], v[40:41] op_sel_hi:[1,0,1]
	s_mov_b64 s[54:55], -1
	s_and_b64 vcc, exec, s[52:53]
	s_cbranch_vccz .LBB0_1082
	s_and_b64 vcc, exec, s[60:61]
	v_ashrrev_i32_e32 v213, 31, v212
	v_mul_f32_e32 v146, v215, v215
	v_mul_f32_e32 v147, v217, v217
	v_mul_f32_e32 v145, v219, v219
	v_mul_f32_e32 v144, v221, v221
	v_cvt_pk_bf16_f32 v124, v214, v215
	v_cvt_pk_bf16_f32 v125, v216, v217
	v_cvt_pk_bf16_f32 v126, v218, v219
	v_cvt_pk_bf16_f32 v127, v220, v221
	s_cbranch_vccz .LBB0_1077
	v_fma_f32 v8, v214, v214, v146
	v_fma_f32 v9, v216, v216, v147
	v_add_f32_e32 v8, v8, v9
	v_fma_f32 v9, v218, v218, v145
	v_add_f32_e32 v8, v9, v8
	v_fma_f32 v9, v220, v220, v144
	v_add_f32_e32 v10, v9, v8
	v_lshlrev_b64 v[8:9], 8, v[212:213]
	v_lshl_add_u64 v[8:9], v[176:177], 0, v[8:9]
	v_cmp_lt_i32_e32 vcc, v231, v226
	v_permlane16_swap_b32_e32 v124, v126
	v_permlane16_swap_b32_e32 v125, v127
	global_store_dwordx4 v[8:9], v[124:127], off
	v_cndmask_b32_e32 v8, v225, v231, vcc
	v_lshlrev_b32_e32 v8, 2, v8
	ds_bpermute_b32 v8, v8, v10
	v_cmp_lt_i32_e32 vcc, v232, v226
	s_waitcnt lgkmcnt(0)
	v_add_f32_e32 v8, v10, v8
	v_cndmask_b32_e32 v9, v225, v232, vcc
	v_lshlrev_b32_e32 v241, 2, v9
	ds_bpermute_b32 v9, v241, v8
	s_and_saveexec_b64 s[54:55], s[40:41]
	s_cbranch_execz .LBB0_1072
	v_readlane_b32 s20, v255, 33
	v_readlane_b32 s21, v255, 34
	s_waitcnt lgkmcnt(0)
	v_add_f32_e32 v8, v8, v9
	v_lshl_add_u64 v[10:11], v[212:213], 2, s[20:21]
	flat_atomic_add_f32 v[10:11], v8

.LBB0_1075:
	v_lshlrev_b64 v[234:235], 6, v[212:213]
	v_lshl_add_u64 v[234:235], v[178:179], 0, v[234:235]
	v_cvt_pk_bf16_f32 v180, v8, v9
	v_cvt_pk_bf16_f32 v181, v10, v11
	v_cvt_pk_bf16_f32 v182, v12, v13
	v_cvt_pk_bf16_f32 v183, v14, v15
	s_nop 1
	v_permlane16_swap_b32_e32 v180, v182
	v_permlane16_swap_b32_e32 v181, v183
	global_store_dwordx4 v[234:235], v[180:183], off

.LBB0_1077:
	s_and_b64 vcc, exec, s[54:55]
	s_cbranch_vccz .LBB0_1081
	v_fmac_f32_e32 v146, v214, v214
	v_fmac_f32_e32 v147, v216, v216
	v_add_f32_e32 v10, v146, v147
	v_fmac_f32_e32 v145, v218, v218
	s_waitcnt lgkmcnt(0)
	v_lshlrev_b64 v[8:9], 9, v[212:213]
	v_add_f32_e32 v10, v145, v10
	v_fmac_f32_e32 v144, v220, v220
	v_add_f32_e32 v12, v144, v10
	v_lshl_add_u64 v[10:11], v[192:193], 0, v[8:9]
	v_mul_f32_e32 v8, v165, v165
	v_mul_f32_e32 v9, v167, v167
	v_fmac_f32_e32 v8, v164, v164
	v_fmac_f32_e32 v9, v166, v166
	v_add_f32_e32 v8, v8, v9
	v_mul_f32_e32 v9, v169, v169
	v_fmac_f32_e32 v9, v168, v168
	v_add_f32_e32 v8, v9, v8
	v_mul_f32_e32 v9, v171, v171
	v_fmac_f32_e32 v9, v170, v170
	v_cmp_lt_i32_e32 vcc, v231, v226
	v_add_f32_e32 v8, v9, v8
	v_add_f32_e32 v8, v12, v8
	v_cndmask_b32_e32 v9, v225, v231, vcc
	v_lshlrev_b32_e32 v9, 2, v9
	ds_bpermute_b32 v9, v9, v8
	v_cmp_lt_i32_e32 vcc, v232, v226
	v_cvt_pk_bf16_f32 v180, v164, v165
	v_cvt_pk_bf16_f32 v181, v166, v167
	v_permlane16_swap_b32_e32 v124, v126
	v_permlane16_swap_b32_e32 v125, v127
	global_store_dwordx4 v[10:11], v[124:127], off
	s_waitcnt lgkmcnt(0)
	v_add_f32_e32 v8, v8, v9
	v_cndmask_b32_e32 v9, v225, v232, vcc
	v_lshlrev_b32_e32 v9, 2, v9
	ds_bpermute_b32 v9, v9, v8
	v_cvt_pk_bf16_f32 v182, v168, v169
	v_cvt_pk_bf16_f32 v183, v170, v171
	s_nop 1
	v_permlane16_swap_b32_e32 v180, v182
	v_permlane16_swap_b32_e32 v181, v183
	global_store_dwordx4 v[10:11], v[180:183], off offset:256
	s_and_saveexec_b64 s[54:55], s[40:41]
	s_cbranch_execz .LBB0_1080
	v_readlane_b32 s20, v255, 31
	v_readlane_b32 s21, v255, 32
	s_waitcnt lgkmcnt(0)
	v_add_f32_e32 v8, v8, v9
	v_lshl_add_u64 v[10:11], v[212:213], 2, s[20:21]
	flat_atomic_add_f32 v[10:11], v8

.LBB0_1084:
	v_fmamk_f32 v8, v211, 0x3a800000, v223
	s_waitcnt lgkmcnt(0)
	v_mul_f32_e32 v9, 0x4b800000, v8
	v_cmp_gt_f32_e32 vcc, s29, v8
	s_mov_b64 s[62:63], -1
	s_nop 0
	v_cndmask_b32_e32 v8, v8, v9, vcc
	v_rsq_f32_e32 v8, v8
	s_nop 0
	v_mul_f32_e32 v9, 0x45800000, v8
	v_cndmask_b32_e32 v12, v8, v9, vcc
	v_pk_fma_f32 v[142:143], v[142:143], v[12:13], v[54:55] op_sel_hi:[1,0,1]
	v_pk_fma_f32 v[140:141], v[140:141], v[12:13], v[52:53] op_sel_hi:[1,0,1]
	v_pk_fma_f32 v[138:139], v[138:139], v[12:13], v[50:51] op_sel_hi:[1,0,1]
	v_pk_fma_f32 v[136:137], v[136:137], v[12:13], v[48:49] op_sel_hi:[1,0,1]
	v_pk_fma_f32 v[10:11], v[134:135], v[12:13], v[46:47] op_sel_hi:[1,0,1]
	v_pk_fma_f32 v[8:9], v[132:133], v[12:13], v[44:45] op_sel_hi:[1,0,1]
	v_pk_fma_f32 v[14:15], v[130:131], v[12:13], v[42:43] op_sel_hi:[1,0,1]
	v_pk_fma_f32 v[12:13], v[128:129], v[12:13], v[40:41] op_sel_hi:[1,0,1]
	v_cndmask_b32_e64 v128, 0, 1, s[52:53]
	v_cmp_ne_u32_e64 s[54:55], 1, v128
	v_cndmask_b32_e64 v128, 0, 1, s[60:61]
	s_andn2_b64 vcc, exec, s[52:53]
	v_cmp_ne_u32_e64 s[52:53], 1, v128
	s_cbranch_vccnz .LBB0_1100
	s_mov_b64 s[60:61], -1
	s_and_b64 vcc, exec, s[52:53]
	v_ashrrev_i32_e32 v211, 31, v210
	v_mul_f32_e32 v162, v141, v141
	v_mul_f32_e32 v163, v143, v143
	v_mul_f32_e32 v161, v137, v137
	v_mul_f32_e32 v160, v139, v139
	v_cvt_pk_bf16_f32 v156, v140, v141
	v_cvt_pk_bf16_f32 v157, v142, v143
	v_cvt_pk_bf16_f32 v158, v136, v137
	v_cvt_pk_bf16_f32 v159, v138, v139
	s_cbranch_vccnz .LBB0_1093
	v_fma_f32 v128, v140, v140, v162
	v_fma_f32 v129, v142, v142, v163
	v_add_f32_e32 v128, v128, v129
	v_fma_f32 v129, v136, v136, v161
	v_add_f32_e32 v128, v129, v128
	v_fma_f32 v129, v138, v138, v160
	v_add_f32_e32 v130, v129, v128
	v_lshlrev_b64 v[128:129], 8, v[210:211]
	v_lshl_add_u64 v[128:129], v[176:177], 0, v[128:129]
	v_cmp_lt_i32_e32 vcc, v231, v226
	v_permlane16_swap_b32_e32 v156, v158
	v_permlane16_swap_b32_e32 v157, v159
	global_store_dwordx4 v[128:129], v[156:159], off
	v_cndmask_b32_e32 v128, v225, v231, vcc
	v_lshlrev_b32_e32 v128, 2, v128
	ds_bpermute_b32 v128, v128, v130
	v_cmp_lt_i32_e32 vcc, v232, v226
	s_waitcnt lgkmcnt(0)
	v_add_f32_e32 v128, v130, v128
	v_cndmask_b32_e32 v129, v225, v232, vcc
	v_lshlrev_b32_e32 v164, 2, v129
	ds_bpermute_b32 v129, v164, v128
	s_and_saveexec_b64 s[60:61], s[40:41]
	s_cbranch_execz .LBB0_1088
	v_readlane_b32 s20, v255, 33
	v_readlane_b32 s21, v255, 34
	s_waitcnt lgkmcnt(0)
	v_add_f32_e32 v128, v128, v129
	v_lshl_add_u64 v[130:131], v[210:211], 2, s[20:21]
	flat_atomic_add_f32 v[130:131], v128

.LBB0_1091:
	v_lshlrev_b64 v[164:165], 6, v[210:211]
	v_lshl_add_u64 v[164:165], v[178:179], 0, v[164:165]
	v_cvt_pk_bf16_f32 v180, v128, v129
	v_cvt_pk_bf16_f32 v181, v130, v131
	v_cvt_pk_bf16_f32 v182, v132, v133
	v_cvt_pk_bf16_f32 v183, v134, v135
	s_nop 1
	v_permlane16_swap_b32_e32 v180, v182
	v_permlane16_swap_b32_e32 v181, v183
	global_store_dwordx4 v[164:165], v[180:183], off

.LBB0_1093:
	s_and_b64 vcc, exec, s[60:61]
	s_cbranch_vccz .LBB0_1097
	v_fmac_f32_e32 v162, v140, v140
	v_fmac_f32_e32 v163, v142, v142
	v_add_f32_e32 v130, v162, v163
	v_fmac_f32_e32 v161, v136, v136
	s_waitcnt lgkmcnt(0)
	v_lshlrev_b64 v[128:129], 9, v[210:211]
	v_add_f32_e32 v130, v161, v130
	v_fmac_f32_e32 v160, v138, v138
	v_add_f32_e32 v132, v160, v130
	v_lshl_add_u64 v[130:131], v[192:193], 0, v[128:129]
	v_mul_f32_e32 v128, v9, v9
	v_mul_f32_e32 v129, v11, v11
	v_fmac_f32_e32 v128, v8, v8
	v_fmac_f32_e32 v129, v10, v10
	v_add_f32_e32 v128, v128, v129
	v_mul_f32_e32 v129, v13, v13
	v_fmac_f32_e32 v129, v12, v12
	v_add_f32_e32 v128, v129, v128
	v_mul_f32_e32 v129, v15, v15
	v_fmac_f32_e32 v129, v14, v14
	v_cmp_lt_i32_e32 vcc, v231, v226
	v_add_f32_e32 v128, v129, v128
	v_add_f32_e32 v128, v132, v128
	v_cndmask_b32_e32 v129, v225, v231, vcc
	v_lshlrev_b32_e32 v129, 2, v129
	ds_bpermute_b32 v129, v129, v128
	v_cmp_lt_i32_e32 vcc, v232, v226
	v_cvt_pk_bf16_f32 v180, v8, v9
	v_cvt_pk_bf16_f32 v181, v10, v11
	v_permlane16_swap_b32_e32 v156, v158
	v_permlane16_swap_b32_e32 v157, v159
	global_store_dwordx4 v[130:131], v[156:159], off
	s_waitcnt lgkmcnt(0)
	v_add_f32_e32 v128, v128, v129
	v_cndmask_b32_e32 v129, v225, v232, vcc
	v_lshlrev_b32_e32 v129, 2, v129
	ds_bpermute_b32 v129, v129, v128
	v_cvt_pk_bf16_f32 v182, v12, v13
	v_cvt_pk_bf16_f32 v183, v14, v15
	s_nop 1
	v_permlane16_swap_b32_e32 v180, v182
	v_permlane16_swap_b32_e32 v181, v183
	global_store_dwordx4 v[130:131], v[180:183], off offset:256
	s_and_saveexec_b64 s[60:61], s[40:41]
	s_cbranch_execz .LBB0_1096
	v_readlane_b32 s20, v255, 31
	v_readlane_b32 s21, v255, 32
	s_waitcnt lgkmcnt(0)
	v_add_f32_e32 v128, v128, v129
	v_lshl_add_u64 v[130:131], v[210:211], 2, s[20:21]
	flat_atomic_add_f32 v[130:131], v128

.LBB0_1103:
	v_fmamk_f32 v128, v209, 0x3a800000, v223
	s_waitcnt lgkmcnt(0)
	v_mul_f32_e32 v129, 0x4b800000, v128
	v_cmp_gt_f32_e32 vcc, s29, v128
	s_mov_b64 s[60:61], -1
	s_nop 0
	v_cndmask_b32_e32 v128, v128, v129, vcc
	v_rsq_f32_e32 v128, v128
	s_nop 0
	v_mul_f32_e32 v129, 0x45800000, v128
	v_cndmask_b32_e32 v136, v128, v129, vcc
	v_pk_fma_f32 v[130:131], v[122:123], v[136:137], v[54:55] op_sel_hi:[1,0,1]
	v_pk_fma_f32 v[128:129], v[120:121], v[136:137], v[52:53] op_sel_hi:[1,0,1]
	v_pk_fma_f32 v[134:135], v[118:119], v[136:137], v[50:51] op_sel_hi:[1,0,1]
	v_pk_fma_f32 v[132:133], v[116:117], v[136:137], v[48:49] op_sel_hi:[1,0,1]
	v_pk_fma_f32 v[114:115], v[114:115], v[136:137], v[46:47] op_sel_hi:[1,0,1]
	v_pk_fma_f32 v[112:113], v[112:113], v[136:137], v[44:45] op_sel_hi:[1,0,1]
	v_pk_fma_f32 v[110:111], v[110:111], v[136:137], v[42:43] op_sel_hi:[1,0,1]
	v_pk_fma_f32 v[108:109], v[108:109], v[136:137], v[40:41] op_sel_hi:[1,0,1]
	s_and_b64 vcc, exec, s[54:55]
	s_cbranch_vccnz .LBB0_1117
	s_and_b64 vcc, exec, s[52:53]
	v_ashrrev_i32_e32 v209, 31, v208
	v_mul_f32_e32 v142, v129, v129
	v_mul_f32_e32 v143, v131, v131
	v_mul_f32_e32 v141, v133, v133
	v_mul_f32_e32 v140, v135, v135
	v_cvt_pk_bf16_f32 v136, v128, v129
	v_cvt_pk_bf16_f32 v137, v130, v131
	v_cvt_pk_bf16_f32 v138, v132, v133
	v_cvt_pk_bf16_f32 v139, v134, v135
	s_cbranch_vccnz .LBB0_1112
	v_fma_f32 v116, v128, v128, v142
	v_fma_f32 v117, v130, v130, v143
	v_add_f32_e32 v116, v116, v117
	v_fma_f32 v117, v132, v132, v141
	v_add_f32_e32 v116, v117, v116
	v_fma_f32 v117, v134, v134, v140
	v_add_f32_e32 v118, v117, v116
	v_lshlrev_b64 v[116:117], 8, v[208:209]
	v_lshl_add_u64 v[116:117], v[176:177], 0, v[116:117]
	v_cmp_lt_i32_e32 vcc, v231, v226
	v_permlane16_swap_b32_e32 v136, v138
	v_permlane16_swap_b32_e32 v137, v139
	global_store_dwordx4 v[116:117], v[136:139], off
	v_cndmask_b32_e32 v116, v225, v231, vcc
	v_lshlrev_b32_e32 v116, 2, v116
	ds_bpermute_b32 v116, v116, v118
	v_cmp_lt_i32_e32 vcc, v232, v226
	s_waitcnt lgkmcnt(0)
	v_add_f32_e32 v116, v118, v116
	v_cndmask_b32_e32 v117, v225, v232, vcc
	v_lshlrev_b32_e32 v148, 2, v117
	ds_bpermute_b32 v117, v148, v116
	s_and_saveexec_b64 s[60:61], s[40:41]
	s_cbranch_execz .LBB0_1107
	v_readlane_b32 s20, v255, 33
	v_readlane_b32 s21, v255, 34
	s_waitcnt lgkmcnt(0)
	v_add_f32_e32 v116, v116, v117
	v_lshl_add_u64 v[118:119], v[208:209], 2, s[20:21]
	flat_atomic_add_f32 v[118:119], v116

.LBB0_1110:
	v_lshlrev_b64 v[148:149], 6, v[208:209]
	v_lshl_add_u64 v[148:149], v[178:179], 0, v[148:149]
	v_cvt_pk_bf16_f32 v180, v116, v117
	v_cvt_pk_bf16_f32 v181, v118, v119
	v_cvt_pk_bf16_f32 v182, v120, v121
	v_cvt_pk_bf16_f32 v183, v122, v123
	s_nop 1
	v_permlane16_swap_b32_e32 v180, v182
	v_permlane16_swap_b32_e32 v181, v183
	global_store_dwordx4 v[148:149], v[180:183], off

.LBB0_1112:
	s_and_b64 vcc, exec, s[60:61]
	s_cbranch_vccz .LBB0_1116
	v_fmac_f32_e32 v142, v128, v128
	v_fmac_f32_e32 v143, v130, v130
	v_add_f32_e32 v118, v142, v143
	v_fmac_f32_e32 v141, v132, v132
	s_waitcnt lgkmcnt(0)
	v_lshlrev_b64 v[116:117], 9, v[208:209]
	v_add_f32_e32 v118, v141, v118
	v_fmac_f32_e32 v140, v134, v134
	v_add_f32_e32 v120, v140, v118
	v_lshl_add_u64 v[118:119], v[192:193], 0, v[116:117]
	v_mul_f32_e32 v116, v113, v113
	v_mul_f32_e32 v117, v115, v115
	v_fmac_f32_e32 v116, v112, v112
	v_fmac_f32_e32 v117, v114, v114
	v_add_f32_e32 v116, v116, v117
	v_mul_f32_e32 v117, v109, v109
	v_fmac_f32_e32 v117, v108, v108
	v_add_f32_e32 v116, v117, v116
	v_mul_f32_e32 v117, v111, v111
	v_fmac_f32_e32 v117, v110, v110
	v_cmp_lt_i32_e32 vcc, v231, v226
	v_add_f32_e32 v116, v117, v116
	v_add_f32_e32 v116, v120, v116
	v_cndmask_b32_e32 v117, v225, v231, vcc
	v_lshlrev_b32_e32 v117, 2, v117
	ds_bpermute_b32 v117, v117, v116
	v_cmp_lt_i32_e32 vcc, v232, v226
	v_cvt_pk_bf16_f32 v180, v112, v113
	v_cvt_pk_bf16_f32 v181, v114, v115
	v_permlane16_swap_b32_e32 v136, v138
	v_permlane16_swap_b32_e32 v137, v139
	global_store_dwordx4 v[118:119], v[136:139], off
	s_waitcnt lgkmcnt(0)
	v_add_f32_e32 v116, v116, v117
	v_cndmask_b32_e32 v117, v225, v232, vcc
	v_lshlrev_b32_e32 v117, 2, v117
	ds_bpermute_b32 v117, v117, v116
	v_cvt_pk_bf16_f32 v182, v108, v109
	v_cvt_pk_bf16_f32 v183, v110, v111
	s_nop 1
	v_permlane16_swap_b32_e32 v180, v182
	v_permlane16_swap_b32_e32 v181, v183
	global_store_dwordx4 v[118:119], v[180:183], off offset:256
	s_and_saveexec_b64 s[60:61], s[40:41]
	s_cbranch_execz .LBB0_1115
	v_readlane_b32 s20, v255, 31
	v_readlane_b32 s21, v255, 32
	s_waitcnt lgkmcnt(0)
	v_add_f32_e32 v116, v116, v117
	v_lshl_add_u64 v[118:119], v[208:209], 2, s[20:21]
	flat_atomic_add_f32 v[118:119], v116

.LBB0_1119:
	s_waitcnt vmcnt(0)
	v_fmamk_f32 v12, v207, 0x3a800000, v223
	v_mul_f32_e32 v13, 0x4b800000, v12
	v_cmp_gt_f32_e32 vcc, s29, v12
	s_mov_b64 s[60:61], -1
	s_nop 0
	v_cndmask_b32_e32 v12, v12, v13, vcc
	v_rsq_f32_e32 v12, v12
	s_nop 0
	v_mul_f32_e32 v13, 0x45800000, v12
	v_cndmask_b32_e32 v112, v12, v13, vcc
	v_pk_fma_f32 v[106:107], v[106:107], v[112:113], v[54:55] op_sel_hi:[1,0,1]
	v_pk_fma_f32 v[104:105], v[104:105], v[112:113], v[52:53] op_sel_hi:[1,0,1]
	v_pk_fma_f32 v[110:111], v[102:103], v[112:113], v[50:51] op_sel_hi:[1,0,1]
	v_pk_fma_f32 v[108:109], v[100:101], v[112:113], v[48:49] op_sel_hi:[1,0,1]
	v_pk_fma_f32 v[14:15], v[94:95], v[112:113], v[46:47] op_sel_hi:[1,0,1]
	v_pk_fma_f32 v[12:13], v[92:93], v[112:113], v[44:45] op_sel_hi:[1,0,1]
	v_pk_fma_f32 v[90:91], v[90:91], v[112:113], v[42:43] op_sel_hi:[1,0,1]
	v_pk_fma_f32 v[88:89], v[88:89], v[112:113], v[40:41] op_sel_hi:[1,0,1]
	s_and_b64 vcc, exec, s[54:55]
	s_cbranch_vccnz .LBB0_1135
	s_and_b64 vcc, exec, s[52:53]
	v_ashrrev_i32_e32 v207, 31, v206
	v_mul_f32_e32 v118, v105, v105
	v_mul_f32_e32 v119, v107, v107
	s_waitcnt lgkmcnt(0)
	v_mul_f32_e32 v117, v109, v109
	v_mul_f32_e32 v116, v111, v111
	v_cvt_pk_bf16_f32 v112, v104, v105
	v_cvt_pk_bf16_f32 v113, v106, v107
	v_cvt_pk_bf16_f32 v114, v108, v109
	v_cvt_pk_bf16_f32 v115, v110, v111
	s_cbranch_vccnz .LBB0_1128
	v_fma_f32 v92, v104, v104, v118
	v_fma_f32 v93, v106, v106, v119
	v_add_f32_e32 v92, v92, v93
	v_fma_f32 v93, v108, v108, v117
	v_add_f32_e32 v92, v93, v92
	v_fma_f32 v93, v110, v110, v116
	v_add_f32_e32 v94, v93, v92
	v_lshlrev_b64 v[92:93], 8, v[206:207]
	v_lshl_add_u64 v[92:93], v[176:177], 0, v[92:93]
	v_cmp_lt_i32_e32 vcc, v231, v226
	v_permlane16_swap_b32_e32 v112, v114
	v_permlane16_swap_b32_e32 v113, v115
	global_store_dwordx4 v[92:93], v[112:115], off
	v_cndmask_b32_e32 v92, v225, v231, vcc
	v_lshlrev_b32_e32 v92, 2, v92
	ds_bpermute_b32 v92, v92, v94
	v_cmp_lt_i32_e32 vcc, v232, v226
	s_waitcnt lgkmcnt(0)
	v_add_f32_e32 v92, v94, v92
	v_cndmask_b32_e32 v93, v225, v232, vcc
	v_lshlrev_b32_e32 v120, 2, v93
	ds_bpermute_b32 v93, v120, v92
	s_and_saveexec_b64 s[60:61], s[40:41]
	s_cbranch_execz .LBB0_1123
	v_readlane_b32 s20, v255, 33
	v_readlane_b32 s21, v255, 34
	s_waitcnt lgkmcnt(0)
	v_add_f32_e32 v92, v92, v93
	v_lshl_add_u64 v[94:95], v[206:207], 2, s[20:21]
	flat_atomic_add_f32 v[94:95], v92

.LBB0_1126:
	v_lshlrev_b64 v[120:121], 6, v[206:207]
	v_lshl_add_u64 v[120:121], v[178:179], 0, v[120:121]
	v_cvt_pk_bf16_f32 v180, v92, v93
	v_cvt_pk_bf16_f32 v181, v94, v95
	v_cvt_pk_bf16_f32 v182, v100, v101
	v_cvt_pk_bf16_f32 v183, v102, v103
	s_nop 1
	v_permlane16_swap_b32_e32 v180, v182
	v_permlane16_swap_b32_e32 v181, v183
	global_store_dwordx4 v[120:121], v[180:183], off

.LBB0_1128:
	s_and_b64 vcc, exec, s[60:61]
	s_cbranch_vccz .LBB0_1132
	v_fmac_f32_e32 v118, v104, v104
	v_fmac_f32_e32 v119, v106, v106
	v_add_f32_e32 v94, v118, v119
	v_fmac_f32_e32 v117, v108, v108
	s_waitcnt lgkmcnt(0)
	v_lshlrev_b64 v[92:93], 9, v[206:207]
	v_add_f32_e32 v94, v117, v94
	v_fmac_f32_e32 v116, v110, v110
	v_add_f32_e32 v100, v116, v94
	v_lshl_add_u64 v[94:95], v[192:193], 0, v[92:93]
	v_mul_f32_e32 v92, v13, v13
	v_mul_f32_e32 v93, v15, v15
	v_fmac_f32_e32 v92, v12, v12
	v_fmac_f32_e32 v93, v14, v14
	v_add_f32_e32 v92, v92, v93
	v_mul_f32_e32 v93, v89, v89
	v_fmac_f32_e32 v93, v88, v88
	v_add_f32_e32 v92, v93, v92
	v_mul_f32_e32 v93, v91, v91
	v_fmac_f32_e32 v93, v90, v90
	v_cmp_lt_i32_e32 vcc, v231, v226
	v_add_f32_e32 v92, v93, v92
	v_add_f32_e32 v92, v100, v92
	v_cndmask_b32_e32 v93, v225, v231, vcc
	v_lshlrev_b32_e32 v93, 2, v93
	ds_bpermute_b32 v93, v93, v92
	v_cmp_lt_i32_e32 vcc, v232, v226
	v_cvt_pk_bf16_f32 v180, v12, v13
	v_cvt_pk_bf16_f32 v181, v14, v15
	v_permlane16_swap_b32_e32 v112, v114
	v_permlane16_swap_b32_e32 v113, v115
	global_store_dwordx4 v[94:95], v[112:115], off
	s_waitcnt lgkmcnt(0)
	v_add_f32_e32 v92, v92, v93
	v_cndmask_b32_e32 v93, v225, v232, vcc
	v_lshlrev_b32_e32 v93, 2, v93
	ds_bpermute_b32 v93, v93, v92
	v_cvt_pk_bf16_f32 v182, v88, v89
	v_cvt_pk_bf16_f32 v183, v90, v91
	s_nop 1
	v_permlane16_swap_b32_e32 v180, v182
	v_permlane16_swap_b32_e32 v181, v183
	global_store_dwordx4 v[94:95], v[180:183], off offset:256
	s_and_saveexec_b64 s[60:61], s[40:41]
	s_cbranch_execz .LBB0_1131
	v_readlane_b32 s20, v255, 31
	v_readlane_b32 s21, v255, 32
	s_waitcnt lgkmcnt(0)
	v_add_f32_e32 v92, v92, v93
	v_lshl_add_u64 v[94:95], v[206:207], 2, s[20:21]
	flat_atomic_add_f32 v[94:95], v92

.LBB0_1138:
	v_fmamk_f32 v100, v205, 0x3a800000, v223
	v_mul_f32_e32 v101, 0x4b800000, v100
	v_cmp_gt_f32_e32 vcc, s29, v100
	s_mov_b64 s[60:61], -1
	s_nop 0
	v_cndmask_b32_e32 v100, v100, v101, vcc
	v_rsq_f32_e32 v100, v100
	s_nop 0
	v_mul_f32_e32 v101, 0x45800000, v100
	v_cndmask_b32_e32 v108, v100, v101, vcc
	v_pk_fma_f32 v[102:103], v[86:87], v[108:109], v[54:55] op_sel_hi:[1,0,1]
	v_pk_fma_f32 v[100:101], v[84:85], v[108:109], v[52:53] op_sel_hi:[1,0,1]
	v_pk_fma_f32 v[106:107], v[82:83], v[108:109], v[50:51] op_sel_hi:[1,0,1]
	v_pk_fma_f32 v[104:105], v[80:81], v[108:109], v[48:49] op_sel_hi:[1,0,1]
	v_pk_fma_f32 v[78:79], v[78:79], v[108:109], v[46:47] op_sel_hi:[1,0,1]
	v_pk_fma_f32 v[76:77], v[76:77], v[108:109], v[44:45] op_sel_hi:[1,0,1]
	v_pk_fma_f32 v[74:75], v[74:75], v[108:109], v[42:43] op_sel_hi:[1,0,1]
	v_pk_fma_f32 v[72:73], v[72:73], v[108:109], v[40:41] op_sel_hi:[1,0,1]
	s_and_b64 vcc, exec, s[54:55]
	s_cbranch_vccnz .LBB0_1152
	s_and_b64 vcc, exec, s[52:53]
	v_ashrrev_i32_e32 v205, 31, v204
	v_mul_f32_e32 v114, v101, v101
	v_mul_f32_e32 v115, v103, v103
	v_mul_f32_e32 v113, v105, v105
	v_mul_f32_e32 v112, v107, v107
	v_cvt_pk_bf16_f32 v108, v100, v101
	v_cvt_pk_bf16_f32 v109, v102, v103
	v_cvt_pk_bf16_f32 v110, v104, v105
	v_cvt_pk_bf16_f32 v111, v106, v107
	s_cbranch_vccnz .LBB0_1147
	v_fma_f32 v80, v100, v100, v114
	v_fma_f32 v81, v102, v102, v115
	v_add_f32_e32 v80, v80, v81
	v_fma_f32 v81, v104, v104, v113
	v_add_f32_e32 v80, v81, v80
	v_fma_f32 v81, v106, v106, v112
	v_add_f32_e32 v82, v81, v80
	v_lshlrev_b64 v[80:81], 8, v[204:205]
	v_lshl_add_u64 v[80:81], v[176:177], 0, v[80:81]
	v_cmp_lt_i32_e32 vcc, v231, v226
	v_permlane16_swap_b32_e32 v108, v110
	v_permlane16_swap_b32_e32 v109, v111
	global_store_dwordx4 v[80:81], v[108:111], off
	v_cndmask_b32_e32 v80, v225, v231, vcc
	v_lshlrev_b32_e32 v80, 2, v80
	ds_bpermute_b32 v80, v80, v82
	v_cmp_lt_i32_e32 vcc, v232, v226
	s_waitcnt lgkmcnt(0)
	v_add_f32_e32 v80, v82, v80
	v_cndmask_b32_e32 v81, v225, v232, vcc
	v_lshlrev_b32_e32 v116, 2, v81
	ds_bpermute_b32 v81, v116, v80
	s_and_saveexec_b64 s[60:61], s[40:41]
	s_cbranch_execz .LBB0_1142
	v_readlane_b32 s20, v255, 33
	v_readlane_b32 s21, v255, 34
	s_waitcnt lgkmcnt(0)
	v_add_f32_e32 v80, v80, v81
	v_lshl_add_u64 v[82:83], v[204:205], 2, s[20:21]
	flat_atomic_add_f32 v[82:83], v80

.LBB0_1145:
	v_lshlrev_b64 v[116:117], 6, v[204:205]
	v_lshl_add_u64 v[116:117], v[178:179], 0, v[116:117]
	v_cvt_pk_bf16_f32 v180, v80, v81
	v_cvt_pk_bf16_f32 v181, v82, v83
	v_cvt_pk_bf16_f32 v182, v84, v85
	v_cvt_pk_bf16_f32 v183, v86, v87
	s_nop 1
	v_permlane16_swap_b32_e32 v180, v182
	v_permlane16_swap_b32_e32 v181, v183
	global_store_dwordx4 v[116:117], v[180:183], off

.LBB0_1147:
	s_and_b64 vcc, exec, s[60:61]
	s_cbranch_vccz .LBB0_1151
	v_fmac_f32_e32 v114, v100, v100
	v_fmac_f32_e32 v115, v102, v102
	v_add_f32_e32 v82, v114, v115
	v_fmac_f32_e32 v113, v104, v104
	s_waitcnt lgkmcnt(0)
	v_lshlrev_b64 v[80:81], 9, v[204:205]
	v_add_f32_e32 v82, v113, v82
	v_fmac_f32_e32 v112, v106, v106
	v_add_f32_e32 v84, v112, v82
	v_lshl_add_u64 v[82:83], v[192:193], 0, v[80:81]
	v_mul_f32_e32 v80, v77, v77
	v_mul_f32_e32 v81, v79, v79
	v_fmac_f32_e32 v80, v76, v76
	v_fmac_f32_e32 v81, v78, v78
	v_add_f32_e32 v80, v80, v81
	v_mul_f32_e32 v81, v73, v73
	v_fmac_f32_e32 v81, v72, v72
	v_add_f32_e32 v80, v81, v80
	v_mul_f32_e32 v81, v75, v75
	v_fmac_f32_e32 v81, v74, v74
	v_cmp_lt_i32_e32 vcc, v231, v226
	v_add_f32_e32 v80, v81, v80
	v_add_f32_e32 v80, v84, v80
	v_cndmask_b32_e32 v81, v225, v231, vcc
	v_lshlrev_b32_e32 v81, 2, v81
	ds_bpermute_b32 v81, v81, v80
	v_cmp_lt_i32_e32 vcc, v232, v226
	v_cvt_pk_bf16_f32 v180, v76, v77
	v_cvt_pk_bf16_f32 v181, v78, v79
	v_permlane16_swap_b32_e32 v108, v110
	v_permlane16_swap_b32_e32 v109, v111
	global_store_dwordx4 v[82:83], v[108:111], off
	s_waitcnt lgkmcnt(0)
	v_add_f32_e32 v80, v80, v81
	v_cndmask_b32_e32 v81, v225, v232, vcc
	v_lshlrev_b32_e32 v81, 2, v81
	ds_bpermute_b32 v81, v81, v80
	v_cvt_pk_bf16_f32 v182, v72, v73
	v_cvt_pk_bf16_f32 v183, v74, v75
	s_nop 1
	v_permlane16_swap_b32_e32 v180, v182
	v_permlane16_swap_b32_e32 v181, v183
	global_store_dwordx4 v[82:83], v[180:183], off offset:256
	s_and_saveexec_b64 s[60:61], s[40:41]
	s_cbranch_execz .LBB0_1150
	v_readlane_b32 s20, v255, 31
	v_readlane_b32 s21, v255, 32
	s_waitcnt lgkmcnt(0)
	v_add_f32_e32 v80, v80, v81
	v_lshl_add_u64 v[82:83], v[204:205], 2, s[20:21]
	flat_atomic_add_f32 v[82:83], v80

.LBB0_1154:
	v_fmamk_f32 v72, v203, 0x3a800000, v223
	v_mul_f32_e32 v73, 0x4b800000, v72
	v_cmp_gt_f32_e32 vcc, s29, v72
	s_mov_b64 s[60:61], -1
	s_nop 0
	v_cndmask_b32_e32 v72, v72, v73, vcc
	v_rsq_f32_e32 v72, v72
	s_nop 0
	v_mul_f32_e32 v73, 0x45800000, v72
	v_cndmask_b32_e32 v80, v72, v73, vcc
	s_waitcnt lgkmcnt(0)
	v_pk_fma_f32 v[74:75], v[70:71], v[80:81], v[54:55] op_sel_hi:[1,0,1]
	v_pk_fma_f32 v[72:73], v[68:69], v[80:81], v[52:53] op_sel_hi:[1,0,1]
	v_pk_fma_f32 v[78:79], v[66:67], v[80:81], v[50:51] op_sel_hi:[1,0,1]
	v_pk_fma_f32 v[76:77], v[64:65], v[80:81], v[48:49] op_sel_hi:[1,0,1]
	v_pk_fma_f32 v[62:63], v[62:63], v[80:81], v[46:47] op_sel_hi:[1,0,1]
	v_pk_fma_f32 v[60:61], v[60:61], v[80:81], v[44:45] op_sel_hi:[1,0,1]
	v_pk_fma_f32 v[58:59], v[58:59], v[80:81], v[42:43] op_sel_hi:[1,0,1]
	v_pk_fma_f32 v[56:57], v[56:57], v[80:81], v[40:41] op_sel_hi:[1,0,1]
	s_and_b64 vcc, exec, s[54:55]
	s_cbranch_vccnz .LBB0_1170
	s_and_b64 vcc, exec, s[52:53]
	v_ashrrev_i32_e32 v203, 31, v202
	v_mul_f32_e32 v86, v73, v73
	v_mul_f32_e32 v87, v75, v75
	v_mul_f32_e32 v85, v77, v77
	v_mul_f32_e32 v84, v79, v79
	v_cvt_pk_bf16_f32 v80, v72, v73
	v_cvt_pk_bf16_f32 v81, v74, v75
	v_cvt_pk_bf16_f32 v82, v76, v77
	v_cvt_pk_bf16_f32 v83, v78, v79
	s_cbranch_vccnz .LBB0_1163
	v_fma_f32 v64, v72, v72, v86
	v_fma_f32 v65, v74, v74, v87
	v_add_f32_e32 v64, v64, v65
	v_fma_f32 v65, v76, v76, v85
	v_add_f32_e32 v64, v65, v64
	v_fma_f32 v65, v78, v78, v84
	v_add_f32_e32 v66, v65, v64
	v_lshlrev_b64 v[64:65], 8, v[202:203]
	v_lshl_add_u64 v[64:65], v[176:177], 0, v[64:65]
	v_cmp_lt_i32_e32 vcc, v231, v226
	v_permlane16_swap_b32_e32 v80, v82
	v_permlane16_swap_b32_e32 v81, v83
	global_store_dwordx4 v[64:65], v[80:83], off
	v_cndmask_b32_e32 v64, v225, v231, vcc
	v_lshlrev_b32_e32 v64, 2, v64
	ds_bpermute_b32 v64, v64, v66
	v_cmp_lt_i32_e32 vcc, v232, v226
	s_waitcnt lgkmcnt(0)
	v_add_f32_e32 v64, v66, v64
	v_cndmask_b32_e32 v65, v225, v232, vcc
	s_waitcnt vmcnt(0)
	v_lshlrev_b32_e32 v88, 2, v65
	ds_bpermute_b32 v65, v88, v64
	s_and_saveexec_b64 s[60:61], s[40:41]
	s_cbranch_execz .LBB0_1158
	v_readlane_b32 s20, v255, 33
	v_readlane_b32 s21, v255, 34
	s_waitcnt lgkmcnt(0)
	v_add_f32_e32 v64, v64, v65
	v_lshl_add_u64 v[66:67], v[202:203], 2, s[20:21]
	flat_atomic_add_f32 v[66:67], v64

.LBB0_1161:
	v_lshlrev_b64 v[88:89], 6, v[202:203]
	v_lshl_add_u64 v[88:89], v[178:179], 0, v[88:89]
	v_cvt_pk_bf16_f32 v180, v64, v65
	v_cvt_pk_bf16_f32 v181, v66, v67
	v_cvt_pk_bf16_f32 v182, v68, v69
	v_cvt_pk_bf16_f32 v183, v70, v71
	s_nop 1
	v_permlane16_swap_b32_e32 v180, v182
	v_permlane16_swap_b32_e32 v181, v183
	global_store_dwordx4 v[88:89], v[180:183], off

.LBB0_1163:
	s_and_b64 vcc, exec, s[60:61]
	s_cbranch_vccz .LBB0_1167
	v_fmac_f32_e32 v86, v72, v72
	v_fmac_f32_e32 v87, v74, v74
	v_add_f32_e32 v66, v86, v87
	v_fmac_f32_e32 v85, v76, v76
	s_waitcnt lgkmcnt(0)
	v_lshlrev_b64 v[64:65], 9, v[202:203]
	v_add_f32_e32 v66, v85, v66
	v_fmac_f32_e32 v84, v78, v78
	v_add_f32_e32 v68, v84, v66
	v_lshl_add_u64 v[66:67], v[192:193], 0, v[64:65]
	v_mul_f32_e32 v64, v61, v61
	v_mul_f32_e32 v65, v63, v63
	v_fmac_f32_e32 v64, v60, v60
	v_fmac_f32_e32 v65, v62, v62
	v_add_f32_e32 v64, v64, v65
	v_mul_f32_e32 v65, v57, v57
	v_fmac_f32_e32 v65, v56, v56
	v_add_f32_e32 v64, v65, v64
	v_mul_f32_e32 v65, v59, v59
	v_fmac_f32_e32 v65, v58, v58
	v_cmp_lt_i32_e32 vcc, v231, v226
	v_add_f32_e32 v64, v65, v64
	v_add_f32_e32 v64, v68, v64
	v_cndmask_b32_e32 v65, v225, v231, vcc
	v_lshlrev_b32_e32 v65, 2, v65
	ds_bpermute_b32 v65, v65, v64
	v_cmp_lt_i32_e32 vcc, v232, v226
	v_cvt_pk_bf16_f32 v180, v60, v61
	v_cvt_pk_bf16_f32 v181, v62, v63
	v_permlane16_swap_b32_e32 v80, v82
	v_permlane16_swap_b32_e32 v81, v83
	global_store_dwordx4 v[66:67], v[80:83], off
	s_waitcnt lgkmcnt(0)
	v_add_f32_e32 v64, v64, v65
	v_cndmask_b32_e32 v65, v225, v232, vcc
	v_lshlrev_b32_e32 v65, 2, v65
	ds_bpermute_b32 v65, v65, v64
	v_cvt_pk_bf16_f32 v182, v56, v57
	v_cvt_pk_bf16_f32 v183, v58, v59
	s_nop 1
	v_permlane16_swap_b32_e32 v180, v182
	v_permlane16_swap_b32_e32 v181, v183
	global_store_dwordx4 v[66:67], v[180:183], off offset:256
	s_and_saveexec_b64 s[60:61], s[40:41]
	s_cbranch_execz .LBB0_1166
	v_readlane_b32 s20, v255, 31
	v_readlane_b32 s21, v255, 32
	s_waitcnt lgkmcnt(0)
	v_add_f32_e32 v64, v64, v65
	v_lshl_add_u64 v[66:67], v[202:203], 2, s[20:21]
	flat_atomic_add_f32 v[66:67], v64

.LBB0_1173:
	v_fmamk_f32 v64, v201, 0x3a800000, v223
	s_waitcnt lgkmcnt(0)
	v_mul_f32_e32 v65, 0x4b800000, v64
	v_cmp_gt_f32_e32 vcc, s29, v64
	s_mov_b64 s[50:51], -1
	s_nop 0
	v_cndmask_b32_e32 v64, v64, v65, vcc
	v_rsq_f32_e32 v64, v64
	s_nop 0
	v_mul_f32_e32 v65, 0x45800000, v64
	v_cndmask_b32_e32 v72, v64, v65, vcc
	v_pk_fma_f32 v[66:67], v[38:39], v[72:73], v[54:55] op_sel_hi:[1,0,1]
	v_pk_fma_f32 v[64:65], v[36:37], v[72:73], v[52:53] op_sel_hi:[1,0,1]
	v_pk_fma_f32 v[70:71], v[34:35], v[72:73], v[50:51] op_sel_hi:[1,0,1]
	v_pk_fma_f32 v[68:69], v[32:33], v[72:73], v[48:49] op_sel_hi:[1,0,1]
	v_pk_fma_f32 v[30:31], v[30:31], v[72:73], v[46:47] op_sel_hi:[1,0,1]
	v_pk_fma_f32 v[28:29], v[28:29], v[72:73], v[44:45] op_sel_hi:[1,0,1]
	v_pk_fma_f32 v[26:27], v[26:27], v[72:73], v[42:43] op_sel_hi:[1,0,1]
	v_pk_fma_f32 v[24:25], v[24:25], v[72:73], v[40:41] op_sel_hi:[1,0,1]
	s_and_b64 vcc, exec, s[54:55]
	s_cbranch_vccnz .LBB0_1187
	s_and_b64 vcc, exec, s[52:53]
	v_ashrrev_i32_e32 v201, 31, v200
	v_mul_f32_e32 v78, v65, v65
	v_mul_f32_e32 v79, v67, v67
	v_mul_f32_e32 v77, v69, v69
	v_mul_f32_e32 v76, v71, v71
	v_cvt_pk_bf16_f32 v72, v64, v65
	v_cvt_pk_bf16_f32 v73, v66, v67
	v_cvt_pk_bf16_f32 v74, v68, v69
	v_cvt_pk_bf16_f32 v75, v70, v71
	s_cbranch_vccnz .LBB0_1182
	v_fma_f32 v32, v64, v64, v78
	v_fma_f32 v33, v66, v66, v79
	v_add_f32_e32 v32, v32, v33
	v_fma_f32 v33, v68, v68, v77
	v_add_f32_e32 v32, v33, v32
	v_fma_f32 v33, v70, v70, v76
	v_add_f32_e32 v34, v33, v32
	v_lshlrev_b64 v[32:33], 8, v[200:201]
	v_lshl_add_u64 v[32:33], v[176:177], 0, v[32:33]
	v_cmp_lt_i32_e32 vcc, v231, v226
	v_permlane16_swap_b32_e32 v72, v74
	v_permlane16_swap_b32_e32 v73, v75
	global_store_dwordx4 v[32:33], v[72:75], off
	v_cndmask_b32_e32 v32, v225, v231, vcc
	v_lshlrev_b32_e32 v32, 2, v32
	ds_bpermute_b32 v32, v32, v34
	v_cmp_lt_i32_e32 vcc, v232, v226
	s_waitcnt lgkmcnt(0)
	v_add_f32_e32 v32, v34, v32
	v_cndmask_b32_e32 v33, v225, v232, vcc
	v_lshlrev_b32_e32 v80, 2, v33
	ds_bpermute_b32 v33, v80, v32
	s_and_saveexec_b64 s[50:51], s[40:41]
	s_cbranch_execz .LBB0_1177
	v_readlane_b32 s20, v255, 33
	v_readlane_b32 s21, v255, 34
	s_waitcnt lgkmcnt(0)
	v_add_f32_e32 v32, v32, v33
	v_lshl_add_u64 v[34:35], v[200:201], 2, s[20:21]
	flat_atomic_add_f32 v[34:35], v32

.LBB0_1180:
	v_lshlrev_b64 v[80:81], 6, v[200:201]
	v_lshl_add_u64 v[80:81], v[178:179], 0, v[80:81]
	v_cvt_pk_bf16_f32 v180, v32, v33
	v_cvt_pk_bf16_f32 v181, v34, v35
	v_cvt_pk_bf16_f32 v182, v36, v37
	v_cvt_pk_bf16_f32 v183, v38, v39
	s_nop 1
	v_permlane16_swap_b32_e32 v180, v182
	v_permlane16_swap_b32_e32 v181, v183
	global_store_dwordx4 v[80:81], v[180:183], off

.LBB0_1182:
	s_and_b64 vcc, exec, s[50:51]
	s_cbranch_vccz .LBB0_1186
	v_fmac_f32_e32 v78, v64, v64
	v_fmac_f32_e32 v79, v66, v66
	v_add_f32_e32 v34, v78, v79
	v_fmac_f32_e32 v77, v68, v68
	s_waitcnt lgkmcnt(0)
	v_lshlrev_b64 v[32:33], 9, v[200:201]
	v_add_f32_e32 v34, v77, v34
	v_fmac_f32_e32 v76, v70, v70
	v_add_f32_e32 v36, v76, v34
	v_lshl_add_u64 v[34:35], v[192:193], 0, v[32:33]
	v_mul_f32_e32 v32, v29, v29
	v_mul_f32_e32 v33, v31, v31
	v_fmac_f32_e32 v32, v28, v28
	v_fmac_f32_e32 v33, v30, v30
	v_add_f32_e32 v32, v32, v33
	v_mul_f32_e32 v33, v25, v25
	v_fmac_f32_e32 v33, v24, v24
	v_add_f32_e32 v32, v33, v32
	v_mul_f32_e32 v33, v27, v27
	v_fmac_f32_e32 v33, v26, v26
	v_cmp_lt_i32_e32 vcc, v231, v226
	v_add_f32_e32 v32, v33, v32
	v_add_f32_e32 v32, v36, v32
	v_cndmask_b32_e32 v33, v225, v231, vcc
	v_lshlrev_b32_e32 v33, 2, v33
	ds_bpermute_b32 v33, v33, v32
	v_cmp_lt_i32_e32 vcc, v232, v226
	v_cvt_pk_bf16_f32 v180, v28, v29
	v_cvt_pk_bf16_f32 v181, v30, v31
	v_permlane16_swap_b32_e32 v72, v74
	v_permlane16_swap_b32_e32 v73, v75
	global_store_dwordx4 v[34:35], v[72:75], off
	s_waitcnt lgkmcnt(0)
	v_add_f32_e32 v32, v32, v33
	v_cndmask_b32_e32 v33, v225, v232, vcc
	v_lshlrev_b32_e32 v33, 2, v33
	ds_bpermute_b32 v33, v33, v32
	v_cvt_pk_bf16_f32 v182, v24, v25
	v_cvt_pk_bf16_f32 v183, v26, v27
	s_nop 1
	v_permlane16_swap_b32_e32 v180, v182
	v_permlane16_swap_b32_e32 v181, v183
	global_store_dwordx4 v[34:35], v[180:183], off offset:256
	s_and_saveexec_b64 s[50:51], s[40:41]
	s_cbranch_execz .LBB0_1185
	v_readlane_b32 s20, v255, 31
	v_readlane_b32 s21, v255, 32
	s_waitcnt lgkmcnt(0)
	v_add_f32_e32 v32, v32, v33
	v_lshl_add_u64 v[34:35], v[200:201], 2, s[20:21]
	flat_atomic_add_f32 v[34:35], v32

.LBB0_1189:
	v_fmamk_f32 v24, v199, 0x3a800000, v223
	v_mul_f32_e32 v25, 0x4b800000, v24
	v_cmp_gt_f32_e32 vcc, s29, v24
	s_mov_b64 s[50:51], -1
	s_nop 0
	v_cndmask_b32_e32 v24, v24, v25, vcc
	v_rsq_f32_e32 v24, v24
	s_nop 0
	v_mul_f32_e32 v25, 0x45800000, v24
	v_cndmask_b32_e32 v32, v24, v25, vcc
	s_waitcnt lgkmcnt(0)
	v_pk_fma_f32 v[26:27], v[22:23], v[32:33], v[54:55] op_sel_hi:[1,0,1]
	v_pk_fma_f32 v[24:25], v[20:21], v[32:33], v[52:53] op_sel_hi:[1,0,1]
	v_pk_fma_f32 v[30:31], v[18:19], v[32:33], v[50:51] op_sel_hi:[1,0,1]
	v_pk_fma_f32 v[28:29], v[16:17], v[32:33], v[48:49] op_sel_hi:[1,0,1]
	v_pk_fma_f32 v[6:7], v[6:7], v[32:33], v[46:47] op_sel_hi:[1,0,1]
	v_pk_fma_f32 v[4:5], v[4:5], v[32:33], v[44:45] op_sel_hi:[1,0,1]
	v_pk_fma_f32 v[2:3], v[2:3], v[32:33], v[42:43] op_sel_hi:[1,0,1]
	v_pk_fma_f32 v[0:1], v[0:1], v[32:33], v[40:41] op_sel_hi:[1,0,1]
	s_and_b64 vcc, exec, s[54:55]
	s_cbranch_vccnz .LBB0_1204
	s_and_b64 vcc, exec, s[52:53]
	v_ashrrev_i32_e32 v199, 31, v198
	v_mul_f32_e32 v38, v25, v25
	v_mul_f32_e32 v39, v27, v27
	v_mul_f32_e32 v37, v29, v29
	v_mul_f32_e32 v36, v31, v31
	v_cvt_pk_bf16_f32 v32, v24, v25
	v_cvt_pk_bf16_f32 v33, v26, v27
	v_cvt_pk_bf16_f32 v34, v28, v29
	v_cvt_pk_bf16_f32 v35, v30, v31
	s_cbranch_vccnz .LBB0_1198
	v_fma_f32 v16, v24, v24, v38
	v_fma_f32 v17, v26, v26, v39
	v_add_f32_e32 v16, v16, v17
	v_fma_f32 v17, v28, v28, v37
	v_add_f32_e32 v16, v17, v16
	v_fma_f32 v17, v30, v30, v36
	v_add_f32_e32 v18, v17, v16
	v_lshlrev_b64 v[16:17], 8, v[198:199]
	v_lshl_add_u64 v[16:17], v[176:177], 0, v[16:17]
	v_cmp_lt_i32_e32 vcc, v231, v226
	v_permlane16_swap_b32_e32 v32, v34
	v_permlane16_swap_b32_e32 v33, v35
	global_store_dwordx4 v[16:17], v[32:35], off
	v_cndmask_b32_e32 v16, v225, v231, vcc
	v_lshlrev_b32_e32 v16, 2, v16
	ds_bpermute_b32 v16, v16, v18
	v_cmp_lt_i32_e32 vcc, v232, v226
	s_waitcnt lgkmcnt(0)
	v_add_f32_e32 v16, v18, v16
	v_cndmask_b32_e32 v17, v225, v232, vcc
	v_lshlrev_b32_e32 v40, 2, v17
	ds_bpermute_b32 v17, v40, v16
	s_and_saveexec_b64 s[50:51], s[40:41]
	s_cbranch_execz .LBB0_1193
	v_readlane_b32 s20, v255, 33
	v_readlane_b32 s21, v255, 34
	s_waitcnt lgkmcnt(0)
	v_add_f32_e32 v16, v16, v17
	v_lshl_add_u64 v[18:19], v[198:199], 2, s[20:21]
	flat_atomic_add_f32 v[18:19], v16

.LBB0_1196:
	v_lshlrev_b64 v[40:41], 6, v[198:199]
	v_lshl_add_u64 v[40:41], v[178:179], 0, v[40:41]
	v_cvt_pk_bf16_f32 v180, v16, v17
	v_cvt_pk_bf16_f32 v181, v18, v19
	v_cvt_pk_bf16_f32 v182, v20, v21
	v_cvt_pk_bf16_f32 v183, v22, v23
	s_nop 1
	v_permlane16_swap_b32_e32 v180, v182
	v_permlane16_swap_b32_e32 v181, v183
	global_store_dwordx4 v[40:41], v[180:183], off

.LBB0_1198:
	s_and_b64 vcc, exec, s[50:51]
	s_cbranch_vccz .LBB0_1202
	v_fmac_f32_e32 v38, v24, v24
	v_fmac_f32_e32 v39, v26, v26
	v_add_f32_e32 v18, v38, v39
	v_fmac_f32_e32 v37, v28, v28
	s_waitcnt lgkmcnt(0)
	v_lshlrev_b64 v[16:17], 9, v[198:199]
	v_add_f32_e32 v18, v37, v18
	v_fmac_f32_e32 v36, v30, v30
	v_add_f32_e32 v20, v36, v18
	v_lshl_add_u64 v[18:19], v[192:193], 0, v[16:17]
	v_mul_f32_e32 v16, v5, v5
	v_mul_f32_e32 v17, v7, v7
	v_fmac_f32_e32 v16, v4, v4
	v_fmac_f32_e32 v17, v6, v6
	v_add_f32_e32 v16, v16, v17
	v_mul_f32_e32 v17, v1, v1
	v_fmac_f32_e32 v17, v0, v0
	v_add_f32_e32 v16, v17, v16
	v_mul_f32_e32 v17, v3, v3
	v_fmac_f32_e32 v17, v2, v2
	v_cmp_lt_i32_e32 vcc, v231, v226
	v_add_f32_e32 v16, v17, v16
	v_add_f32_e32 v16, v20, v16
	v_cndmask_b32_e32 v17, v225, v231, vcc
	v_lshlrev_b32_e32 v17, 2, v17
	ds_bpermute_b32 v17, v17, v16
	v_cmp_lt_i32_e32 vcc, v232, v226
	v_cvt_pk_bf16_f32 v180, v4, v5
	v_cvt_pk_bf16_f32 v181, v6, v7
	v_permlane16_swap_b32_e32 v32, v34
	v_permlane16_swap_b32_e32 v33, v35
	global_store_dwordx4 v[18:19], v[32:35], off
	s_waitcnt lgkmcnt(0)
	v_add_f32_e32 v16, v16, v17
	v_cndmask_b32_e32 v17, v225, v232, vcc
	v_lshlrev_b32_e32 v17, 2, v17
	ds_bpermute_b32 v17, v17, v16
	v_cvt_pk_bf16_f32 v182, v0, v1
	v_cvt_pk_bf16_f32 v183, v2, v3
	s_nop 1
	v_permlane16_swap_b32_e32 v180, v182
	v_permlane16_swap_b32_e32 v181, v183
	global_store_dwordx4 v[18:19], v[180:183], off offset:256
	s_and_saveexec_b64 s[50:51], s[40:41]
	s_cbranch_execz .LBB0_1201
	v_readlane_b32 s20, v255, 31
	v_readlane_b32 s21, v255, 32
	s_waitcnt lgkmcnt(0)
	v_add_f32_e32 v16, v16, v17
	v_lshl_add_u64 v[18:19], v[198:199], 2, s[20:21]
	flat_atomic_add_f32 v[18:19], v16
